# attention loops: wave-group dependent s_setprio (waves 0-3: MFMA 3 / softmax 1, waves 4-7: MFMA 2 / softmax 0) to run the two waves of a SIMD out of phase
# speedup vs baseline: 1.0148x; 1.0057x over previous
.LBB0_340:
	v_cmp_gt_u32_e32 vcc, 0x100, v206
	s_setprio 2
	s_cbranch_vccz .Lprio_2
	s_setprio 3
.Lprio_2:
	v_add_u32_e32 v101, s4, v96
	s_waitcnt vmcnt(0)
	ds_read_b128 v[34:37], v101
	v_add_u32_e32 v100, s4, v95
	ds_read_b128 v[104:107], v100
	ds_read_b128 v[50:53], v101 offset:4096
	v_add_u32_e32 v99, s4, v94
	v_add_u32_e32 v98, s4, v93
	s_waitcnt lgkmcnt(0)
	v_mfma_f32_32x32x16_bf16 v[34:49], v[34:37], v[66:69], 0
	v_mfma_f32_32x32x16_bf16 v[34:49], v[104:107], v[70:73], v[34:49]
	ds_read_b128 v[104:107], v100 offset:4096
	v_mfma_f32_32x32x16_bf16 v[50:65], v[50:53], v[66:69], 0
	s_waitcnt lgkmcnt(0)
	v_mfma_f32_32x32x16_bf16 v[50:65], v[104:107], v[70:73], v[50:65]
	ds_read_b128 v[104:107], v99
	s_waitcnt lgkmcnt(0)
	v_mfma_f32_32x32x16_bf16 v[34:49], v[104:107], v[74:77], v[34:49]
	ds_read_b128 v[104:107], v99 offset:4096
	s_waitcnt lgkmcnt(0)
	v_mfma_f32_32x32x16_bf16 v[50:65], v[104:107], v[74:77], v[50:65]
	ds_read_b128 v[104:107], v98 offset:4096
	s_waitcnt lgkmcnt(0)
	v_mfma_f32_32x32x16_bf16 v[50:65], v[104:107], v[78:81], v[50:65]
	ds_read_b128 v[104:107], v98
	s_waitcnt lgkmcnt(0)
	v_mfma_f32_32x32x16_bf16 v[34:49], v[104:107], v[78:81], v[34:49]
	v_cmp_gt_u32_e32 vcc, 0x100, v206
	s_setprio 0
	s_cbranch_vccz .Lprio_1
	s_setprio 1
.Lprio_1:
	s_nop 8
	v_max_f32_e32 v0, v51, v51
	s_nop 1
	v_max_f32_e32 v97, v35, v35
	v_max_f32_e32 v0, v97, v0
	v_max_f32_e32 v97, v52, v52
	v_max_f32_e32 v104, v36, v36
	v_max_f32_e32 v97, v104, v97
	v_max_f32_e32 v104, v53, v53
	v_max_f32_e32 v105, v37, v37
	v_max3_f32 v0, v34, v50, v0
	v_max_f32_e32 v104, v105, v104
	v_max3_f32 v0, v0, v97, v104
	v_max_f32_e32 v97, v54, v54
	v_max_f32_e32 v104, v38, v38
	v_max_f32_e32 v97, v104, v97
	v_max_f32_e32 v104, v55, v55
	v_max_f32_e32 v105, v39, v39
	v_max_f32_e32 v104, v105, v104
	v_max3_f32 v0, v0, v97, v104
	v_max_f32_e32 v97, v56, v56
	v_max_f32_e32 v104, v40, v40
	v_max_f32_e32 v97, v104, v97
	v_max_f32_e32 v104, v57, v57
	v_max_f32_e32 v105, v41, v41
	v_max_f32_e32 v104, v105, v104
	v_max3_f32 v0, v0, v97, v104
	v_max_f32_e32 v97, v58, v58
	v_max_f32_e32 v104, v42, v42
	v_max_f32_e32 v97, v104, v97
	v_max_f32_e32 v104, v59, v59
	v_max_f32_e32 v105, v43, v43
	v_max_f32_e32 v104, v105, v104
	v_max3_f32 v0, v0, v97, v104
	v_max_f32_e32 v97, v60, v60
	v_max_f32_e32 v104, v44, v44
	v_max_f32_e32 v97, v104, v97
	v_max_f32_e32 v104, v61, v61
	v_max_f32_e32 v105, v45, v45
	v_max_f32_e32 v104, v105, v104
	v_max3_f32 v0, v0, v97, v104
	v_max_f32_e32 v97, v62, v62
	v_max_f32_e32 v104, v46, v46
	v_max_f32_e32 v97, v104, v97
	v_max_f32_e32 v104, v63, v63
	v_max_f32_e32 v105, v47, v47
	v_max_f32_e32 v104, v105, v104
	v_max3_f32 v0, v0, v97, v104
	v_max_f32_e32 v97, v64, v64
	v_max_f32_e32 v104, v48, v48
	v_max_f32_e32 v97, v104, v97
	v_max_f32_e32 v104, v65, v65
	v_max_f32_e32 v105, v49, v49
	v_max_f32_e32 v104, v105, v104
	v_max3_f32 v0, v0, v97, v104
	v_and_b32_e32 v104, 64, v221
	v_xor_b32_e32 v97, 32, v221
	v_add_u32_e32 v104, 64, v104
	v_cmp_lt_i32_e32 vcc, v97, v104
	s_nop 1
	v_cndmask_b32_e32 v97, v221, v97, vcc
	v_lshlrev_b32_e32 v104, 2, v97
	ds_bpermute_b32 v97, v104, v0
	s_waitcnt lgkmcnt(0)
	v_max3_f32 v97, v103, v0, v97
	v_sub_f32_e32 v0, v34, v97
	v_exp_f32_e32 v34, v0
	v_sub_f32_e32 v0, v50, v97
	v_exp_f32_e32 v50, v0
	v_sub_f32_e32 v0, v35, v97
	v_exp_f32_e32 v35, v0
	v_sub_f32_e32 v0, v51, v97
	v_exp_f32_e32 v51, v0
	v_sub_f32_e32 v36, v36, v97
	v_sub_f32_e32 v52, v52, v97
	v_exp_f32_e32 v36, v36
	v_exp_f32_e32 v52, v52
	v_sub_f32_e32 v0, v103, v97
	v_add_f32_e32 v103, v34, v50
	v_add_f32_e32 v103, 0, v103
	v_add_f32_e32 v105, v35, v51
	v_add_f32_e32 v103, v105, v103
	v_add_f32_e32 v105, v36, v52
	v_sub_f32_e32 v38, v38, v97
	v_sub_f32_e32 v37, v37, v97
	v_sub_f32_e32 v53, v53, v97
	v_add_f32_e32 v105, v105, v103
	v_exp_f32_e32 v103, v38
	v_sub_f32_e32 v38, v54, v97
	v_exp_f32_e32 v37, v37
	v_exp_f32_e32 v53, v53
	v_exp_f32_e32 v54, v38
	v_sub_f32_e32 v38, v39, v97
	v_exp_f32_e32 v39, v38
	v_sub_f32_e32 v38, v55, v97
	v_exp_f32_e32 v55, v38
	v_sub_f32_e32 v40, v40, v97
	v_sub_f32_e32 v56, v56, v97
	v_exp_f32_e32 v40, v40
	v_exp_f32_e32 v56, v56
	v_sub_f32_e32 v41, v41, v97
	v_sub_f32_e32 v57, v57, v97
	v_add_f32_e32 v106, v37, v53
	v_exp_f32_e32 v41, v41
	v_exp_f32_e32 v57, v57
	v_sub_f32_e32 v42, v42, v97
	v_sub_f32_e32 v58, v58, v97
	v_add_f32_e32 v38, v106, v105
	v_add_f32_e32 v105, v103, v54
	v_exp_f32_e32 v42, v42
	v_exp_f32_e32 v58, v58
	v_sub_f32_e32 v43, v43, v97
	v_sub_f32_e32 v59, v59, v97
	v_add_f32_e32 v38, v105, v38
	v_add_f32_e32 v105, v39, v55
	v_exp_f32_e32 v43, v43
	v_exp_f32_e32 v59, v59
	v_sub_f32_e32 v44, v44, v97
	v_sub_f32_e32 v60, v60, v97
	v_add_f32_e32 v38, v105, v38
	v_add_f32_e32 v105, v40, v56
	v_exp_f32_e32 v44, v44
	v_exp_f32_e32 v60, v60
	v_sub_f32_e32 v45, v45, v97
	v_sub_f32_e32 v61, v61, v97
	v_add_f32_e32 v38, v105, v38
	v_add_f32_e32 v105, v41, v57
	v_exp_f32_e32 v45, v45
	v_exp_f32_e32 v61, v61
	v_sub_f32_e32 v46, v46, v97
	v_sub_f32_e32 v62, v62, v97
	v_add_f32_e32 v38, v105, v38
	v_add_f32_e32 v105, v42, v58
	v_exp_f32_e32 v46, v46
	v_exp_f32_e32 v62, v62
	v_sub_f32_e32 v47, v47, v97
	v_sub_f32_e32 v63, v63, v97
	v_add_f32_e32 v38, v105, v38
	v_add_f32_e32 v105, v43, v59
	v_exp_f32_e32 v47, v47
	v_exp_f32_e32 v63, v63
	v_sub_f32_e32 v48, v48, v97
	v_sub_f32_e32 v64, v64, v97
	v_add_f32_e32 v38, v105, v38
	v_add_f32_e32 v105, v44, v60
	v_exp_f32_e32 v48, v48
	v_exp_f32_e32 v64, v64
	v_sub_f32_e32 v49, v49, v97
	v_sub_f32_e32 v65, v65, v97
	v_add_f32_e32 v38, v105, v38
	v_add_f32_e32 v105, v45, v61
	v_exp_f32_e32 v49, v49
	v_exp_f32_e32 v65, v65
	v_add_f32_e32 v38, v105, v38
	v_add_f32_e32 v105, v46, v62
	v_add_f32_e32 v38, v105, v38
	v_add_f32_e32 v105, v47, v63
	v_add_f32_e32 v38, v105, v38
	v_add_f32_e32 v105, v48, v64
	v_add_f32_e32 v38, v105, v38
	v_add_f32_e32 v105, v49, v65
	v_add_f32_e32 v38, v105, v38
	v_exp_f32_e32 v0, v0
	ds_bpermute_b32 v104, v104, v38
	v_cmp_neq_f32_e32 vcc, 1.0, v0
	s_cbranch_vccz .LBB0_342
	v_pk_mul_f32 v[32:33], v[32:33], v[0:1] op_sel_hi:[1,0]
	v_pk_mul_f32 v[30:31], v[30:31], v[0:1] op_sel_hi:[1,0]
	v_pk_mul_f32 v[28:29], v[28:29], v[0:1] op_sel_hi:[1,0]
	v_pk_mul_f32 v[26:27], v[26:27], v[0:1] op_sel_hi:[1,0]
	v_pk_mul_f32 v[24:25], v[24:25], v[0:1] op_sel_hi:[1,0]
	v_pk_mul_f32 v[22:23], v[22:23], v[0:1] op_sel_hi:[1,0]
	v_pk_mul_f32 v[20:21], v[20:21], v[0:1] op_sel_hi:[1,0]
	v_pk_mul_f32 v[18:19], v[18:19], v[0:1] op_sel_hi:[1,0]
	v_pk_mul_f32 v[16:17], v[16:17], v[0:1] op_sel_hi:[1,0]
	v_pk_mul_f32 v[14:15], v[14:15], v[0:1] op_sel_hi:[1,0]
	v_pk_mul_f32 v[12:13], v[12:13], v[0:1] op_sel_hi:[1,0]
	v_pk_mul_f32 v[10:11], v[10:11], v[0:1] op_sel_hi:[1,0]
	v_pk_mul_f32 v[8:9], v[8:9], v[0:1] op_sel_hi:[1,0]
	v_pk_mul_f32 v[6:7], v[6:7], v[0:1] op_sel_hi:[1,0]
	v_pk_mul_f32 v[4:5], v[4:5], v[0:1] op_sel_hi:[1,0]
	v_pk_mul_f32 v[2:3], v[2:3], v[0:1] op_sel_hi:[1,0]

.Lprio_5:
	s_mul_i32 s0, s5, 0xa000
	v_add_u32_e32 v185, s0, v176
	v_add_u32_e32 v187, s0, v178
	v_add_u32_e32 v192, s0, v180
	v_add_u32_e32 v193, s0, v182
	ds_read_b128 v[196:199], v185
	ds_read_b128 v[200:203], v187
	ds_read_b128 v[232:235], v185 offset:12288
	ds_read_b128 v[236:239], v187 offset:12288
	ds_read_b128 v[240:243], v192
	s_waitcnt lgkmcnt(4)
	v_mfma_f32_32x32x16_bf16 v[66:81], v[196:199], v[98:101], 0
	ds_read_b128 v[244:247], v192 offset:12288
	s_waitcnt lgkmcnt(4)
	v_mfma_f32_32x32x16_bf16 v[66:81], v[200:203], v[102:105], v[66:81]
	ds_read_b128 v[196:199], v193
	s_waitcnt lgkmcnt(4)
	v_mfma_f32_32x32x16_bf16 v[82:97], v[232:235], v[98:101], 0
	ds_read_b128 v[200:203], v193 offset:12288
	s_waitcnt lgkmcnt(4)
	v_mfma_f32_32x32x16_bf16 v[82:97], v[236:239], v[102:105], v[82:97]
	ds_read_b128 v[232:235], v185 offset:128
	s_waitcnt lgkmcnt(4)
	v_mfma_f32_32x32x16_bf16 v[66:81], v[240:243], v[106:109], v[66:81]
	ds_read_b128 v[236:239], v185 offset:12416
	s_waitcnt lgkmcnt(4)
	v_mfma_f32_32x32x16_bf16 v[82:97], v[244:247], v[106:109], v[82:97]
	ds_read_b128 v[240:243], v187 offset:128
	s_waitcnt lgkmcnt(4)
	v_mfma_f32_32x32x16_bf16 v[66:81], v[196:199], v[110:113], v[66:81]
	ds_read_b128 v[244:247], v187 offset:12416
	s_waitcnt lgkmcnt(4)
	v_mfma_f32_32x32x16_bf16 v[82:97], v[200:203], v[110:113], v[82:97]
	ds_read_b128 v[196:199], v192 offset:128
	s_waitcnt lgkmcnt(4)
	v_mfma_f32_32x32x16_bf16 v[66:81], v[232:235], v[114:117], v[66:81]
	ds_read_b128 v[200:203], v192 offset:12416
	s_waitcnt lgkmcnt(4)
	v_mfma_f32_32x32x16_bf16 v[82:97], v[236:239], v[114:117], v[82:97]
	ds_read_b128 v[232:235], v193 offset:128
	s_waitcnt lgkmcnt(4)
	v_mfma_f32_32x32x16_bf16 v[66:81], v[240:243], v[118:121], v[66:81]
	ds_read_b128 v[236:239], v193 offset:12416
	s_waitcnt lgkmcnt(4)
	v_mfma_f32_32x32x16_bf16 v[82:97], v[244:247], v[118:121], v[82:97]
	ds_read_b128 v[240:243], v185 offset:256
	s_waitcnt lgkmcnt(4)
	v_mfma_f32_32x32x16_bf16 v[66:81], v[196:199], v[122:125], v[66:81]
	ds_read_b128 v[244:247], v185 offset:12544
	s_waitcnt lgkmcnt(4)
	v_mfma_f32_32x32x16_bf16 v[82:97], v[200:203], v[122:125], v[82:97]
	ds_read_b128 v[196:199], v187 offset:256
	s_waitcnt lgkmcnt(4)
	v_mfma_f32_32x32x16_bf16 v[66:81], v[232:235], v[126:129], v[66:81]
	ds_read_b128 v[200:203], v187 offset:12544
	s_waitcnt lgkmcnt(4)
	v_mfma_f32_32x32x16_bf16 v[82:97], v[236:239], v[126:129], v[82:97]
	ds_read_b128 v[232:235], v192 offset:256
	s_waitcnt lgkmcnt(4)
	v_mfma_f32_32x32x16_bf16 v[66:81], v[240:243], v[130:133], v[66:81]
	ds_read_b128 v[236:239], v192 offset:12544
	s_waitcnt lgkmcnt(4)
	v_mfma_f32_32x32x16_bf16 v[82:97], v[244:247], v[130:133], v[82:97]
	ds_read_b128 v[240:243], v193 offset:12544
	s_waitcnt lgkmcnt(4)
	v_mfma_f32_32x32x16_bf16 v[66:81], v[196:199], v[134:137], v[66:81]
	ds_read_b128 v[244:247], v193 offset:256
	s_waitcnt lgkmcnt(4)
	v_mfma_f32_32x32x16_bf16 v[82:97], v[200:203], v[134:137], v[82:97]
	s_waitcnt lgkmcnt(3)
	v_mfma_f32_32x32x16_bf16 v[66:81], v[232:235], v[138:141], v[66:81]
	s_waitcnt lgkmcnt(2)
	v_mfma_f32_32x32x16_bf16 v[82:97], v[236:239], v[138:141], v[82:97]
	s_waitcnt lgkmcnt(1)
	v_mfma_f32_32x32x16_bf16 v[82:97], v[240:243], v[142:145], v[82:97]
	s_waitcnt lgkmcnt(0)
	v_mfma_f32_32x32x16_bf16 v[66:81], v[244:247], v[142:145], v[66:81]
	v_cmp_gt_u32_e32 vcc, 0x100, v206
	s_setprio 0
	s_cbranch_vccz .Lprio_4
	s_setprio 1
.Lprio_4:
	s_nop 1
	s_nop 8
	v_max_f32_e32 v185, v83, v83
	s_nop 1
	v_max_f32_e32 v187, v67, v67
	v_max_f32_e32 v185, v187, v185
	v_max_f32_e32 v187, v84, v84
	v_max_f32_e32 v188, v68, v68
	v_max_f32_e32 v187, v188, v187
	v_max_f32_e32 v188, v85, v85
	v_max_f32_e32 v189, v69, v69
	v_max3_f32 v185, v66, v82, v185
	v_max_f32_e32 v188, v189, v188
	v_max3_f32 v185, v185, v187, v188
	v_max_f32_e32 v187, v86, v86
	v_max_f32_e32 v188, v70, v70
	v_max_f32_e32 v187, v188, v187
	v_max_f32_e32 v188, v87, v87
	v_max_f32_e32 v189, v71, v71
	v_max_f32_e32 v188, v189, v188
	v_max3_f32 v185, v185, v187, v188
	v_max_f32_e32 v187, v88, v88
	v_max_f32_e32 v188, v72, v72
	v_max_f32_e32 v187, v188, v187
	v_max_f32_e32 v188, v89, v89
	v_max_f32_e32 v189, v73, v73
	v_max_f32_e32 v188, v189, v188
	v_max3_f32 v185, v185, v187, v188
	v_max_f32_e32 v187, v90, v90
	v_max_f32_e32 v188, v74, v74
	v_max_f32_e32 v187, v188, v187
	v_max_f32_e32 v188, v91, v91
	v_max_f32_e32 v189, v75, v75
	v_max_f32_e32 v188, v189, v188
	v_max3_f32 v185, v185, v187, v188
	v_max_f32_e32 v187, v92, v92
	v_max_f32_e32 v188, v76, v76
	v_max_f32_e32 v187, v188, v187
	v_max_f32_e32 v188, v93, v93
	v_max_f32_e32 v189, v77, v77
	v_max_f32_e32 v188, v189, v188
	v_max3_f32 v185, v185, v187, v188
	v_max_f32_e32 v187, v94, v94
	v_max_f32_e32 v188, v78, v78
	v_max_f32_e32 v187, v188, v187
	v_max_f32_e32 v188, v95, v95
	v_max_f32_e32 v189, v79, v79
	v_max_f32_e32 v188, v189, v188
	v_max3_f32 v185, v185, v187, v188
	v_max_f32_e32 v187, v96, v96
	v_max_f32_e32 v188, v80, v80
	v_max_f32_e32 v187, v188, v187
	v_max_f32_e32 v188, v97, v97
	v_max_f32_e32 v189, v81, v81
	v_max_f32_e32 v188, v189, v188
	v_max3_f32 v185, v185, v187, v188
	v_and_b32_e32 v188, 64, v221
	v_xor_b32_e32 v187, 32, v221
	v_add_u32_e32 v188, 64, v188
	v_cmp_lt_i32_e32 vcc, v187, v188
	s_nop 1
	v_cndmask_b32_e32 v187, v221, v187, vcc
	v_lshlrev_b32_e32 v193, 2, v187
	ds_bpermute_b32 v187, v193, v185
	s_waitcnt lgkmcnt(0)
	v_max3_f32 v185, v186, v185, v187
	v_sub_f32_e32 v66, v66, v185
	v_exp_f32_e32 v187, v66
	v_sub_f32_e32 v66, v82, v185
	v_exp_f32_e32 v188, v66
	v_sub_f32_e32 v66, v67, v185
	v_exp_f32_e32 v67, v66
	v_sub_f32_e32 v66, v83, v185
	v_exp_f32_e32 v83, v66
	v_sub_f32_e32 v68, v68, v185
	v_sub_f32_e32 v84, v84, v185
	v_exp_f32_e32 v68, v68
	v_exp_f32_e32 v84, v84
	v_add_f32_e32 v82, v187, v188
	v_sub_f32_e32 v69, v69, v185
	v_sub_f32_e32 v85, v85, v185
	v_sub_f32_e32 v66, v186, v185
	v_add_f32_e32 v82, 0, v82
	v_add_f32_e32 v186, v67, v83
	v_exp_f32_e32 v69, v69
	v_exp_f32_e32 v85, v85
	v_add_f32_e32 v82, v186, v82
	v_add_f32_e32 v186, v68, v84
	v_sub_f32_e32 v70, v70, v185
	v_add_f32_e32 v82, v186, v82
	v_exp_f32_e32 v186, v70
	v_sub_f32_e32 v70, v86, v185
	v_exp_f32_e32 v86, v70
	v_sub_f32_e32 v70, v71, v185
	v_add_f32_e32 v190, v69, v85
	v_exp_f32_e32 v189, v70
	v_sub_f32_e32 v70, v87, v185
	v_sub_f32_e32 v72, v72, v185
	v_exp_f32_e32 v87, v70
	v_add_f32_e32 v70, v190, v82
	v_exp_f32_e32 v190, v72
	v_sub_f32_e32 v72, v88, v185
	v_exp_f32_e32 v88, v72
	v_add_f32_e32 v71, v186, v86
	v_add_f32_e32 v70, v71, v70
	v_add_f32_e32 v71, v189, v87
	v_sub_f32_e32 v72, v73, v185
	v_exp_f32_e32 v73, v72
	v_sub_f32_e32 v72, v89, v185
	v_add_f32_e32 v70, v71, v70
	v_add_f32_e32 v71, v190, v88
	v_exp_f32_e32 v89, v72
	v_add_f32_e32 v82, v71, v70
	v_sub_f32_e32 v70, v74, v185
	v_sub_f32_e32 v71, v90, v185
	v_exp_f32_e32 v70, v70
	v_exp_f32_e32 v71, v71
	v_sub_f32_e32 v72, v75, v185
	v_sub_f32_e32 v74, v91, v185
	v_exp_f32_e32 v72, v72
	v_exp_f32_e32 v75, v74
	v_sub_f32_e32 v76, v76, v185
	v_sub_f32_e32 v90, v92, v185
	v_sub_f32_e32 v78, v78, v185
	v_exp_f32_e32 v76, v76
	v_exp_f32_e32 v90, v90
	v_sub_f32_e32 v77, v77, v185
	v_sub_f32_e32 v91, v93, v185
	v_exp_f32_e32 v92, v78
	v_sub_f32_e32 v78, v94, v185
	v_add_f32_e32 v191, v73, v89
	v_exp_f32_e32 v77, v77
	v_exp_f32_e32 v91, v91
	v_exp_f32_e32 v93, v78
	v_sub_f32_e32 v78, v79, v185
	v_sub_f32_e32 v79, v80, v185
	v_add_f32_e32 v74, v191, v82
	v_add_f32_e32 v82, v70, v71
	v_exp_f32_e32 v94, v78
	v_sub_f32_e32 v78, v95, v185
	v_exp_f32_e32 v191, v79
	v_sub_f32_e32 v79, v96, v185
	v_add_f32_e32 v74, v82, v74
	v_add_f32_e32 v82, v72, v75
	v_exp_f32_e32 v95, v78
	v_exp_f32_e32 v96, v79
	v_sub_f32_e32 v79, v81, v185
	v_add_f32_e32 v74, v82, v74
	v_add_f32_e32 v82, v76, v90
	v_exp_f32_e32 v192, v79
	v_sub_f32_e32 v79, v97, v185
	v_add_f32_e32 v74, v82, v74
	v_add_f32_e32 v82, v77, v91
	v_exp_f32_e32 v97, v79
	v_add_f32_e32 v74, v82, v74
	v_add_f32_e32 v78, v92, v93
	v_add_f32_e32 v74, v78, v74
	v_add_f32_e32 v78, v94, v95
	v_add_f32_e32 v74, v78, v74
	v_add_f32_e32 v78, v191, v96
	v_add_f32_e32 v74, v78, v74
	v_add_f32_e32 v78, v192, v97
	v_add_f32_e32 v74, v78, v74
	v_exp_f32_e32 v66, v66
	ds_bpermute_b32 v78, v193, v74
	v_cmp_neq_f32_e32 vcc, 1.0, v66
	s_cbranch_vccz .LBB0_354
	v_pk_mul_f32 v[64:65], v[64:65], v[66:67] op_sel_hi:[1,0]
	v_pk_mul_f32 v[62:63], v[62:63], v[66:67] op_sel_hi:[1,0]
	v_pk_mul_f32 v[60:61], v[60:61], v[66:67] op_sel_hi:[1,0]
	v_pk_mul_f32 v[58:59], v[58:59], v[66:67] op_sel_hi:[1,0]
	v_pk_mul_f32 v[56:57], v[56:57], v[66:67] op_sel_hi:[1,0]
	v_pk_mul_f32 v[54:55], v[54:55], v[66:67] op_sel_hi:[1,0]
	v_pk_mul_f32 v[52:53], v[52:53], v[66:67] op_sel_hi:[1,0]
	v_pk_mul_f32 v[50:51], v[50:51], v[66:67] op_sel_hi:[1,0]
	v_pk_mul_f32 v[48:49], v[48:49], v[66:67] op_sel_hi:[1,0]
	v_pk_mul_f32 v[46:47], v[46:47], v[66:67] op_sel_hi:[1,0]
	v_pk_mul_f32 v[44:45], v[44:45], v[66:67] op_sel_hi:[1,0]
	v_pk_mul_f32 v[42:43], v[42:43], v[66:67] op_sel_hi:[1,0]
	v_pk_mul_f32 v[40:41], v[40:41], v[66:67] op_sel_hi:[1,0]
	v_pk_mul_f32 v[38:39], v[38:39], v[66:67] op_sel_hi:[1,0]
	v_pk_mul_f32 v[36:37], v[36:37], v[66:67] op_sel_hi:[1,0]
	v_pk_mul_f32 v[34:35], v[34:35], v[66:67] op_sel_hi:[1,0]
	v_pk_mul_f32 v[32:33], v[32:33], v[66:67] op_sel_hi:[1,0]
	v_pk_mul_f32 v[30:31], v[30:31], v[66:67] op_sel_hi:[1,0]
	v_pk_mul_f32 v[28:29], v[28:29], v[66:67] op_sel_hi:[1,0]
	v_pk_mul_f32 v[26:27], v[26:27], v[66:67] op_sel_hi:[1,0]
	v_pk_mul_f32 v[24:25], v[24:25], v[66:67] op_sel_hi:[1,0]
	v_pk_mul_f32 v[22:23], v[22:23], v[66:67] op_sel_hi:[1,0]
	v_pk_mul_f32 v[20:21], v[20:21], v[66:67] op_sel_hi:[1,0]
	v_pk_mul_f32 v[18:19], v[18:19], v[66:67] op_sel_hi:[1,0]
	v_pk_mul_f32 v[16:17], v[16:17], v[66:67] op_sel_hi:[1,0]
	v_pk_mul_f32 v[14:15], v[14:15], v[66:67] op_sel_hi:[1,0]
	v_pk_mul_f32 v[12:13], v[12:13], v[66:67] op_sel_hi:[1,0]
	v_pk_mul_f32 v[10:11], v[10:11], v[66:67] op_sel_hi:[1,0]
	v_pk_mul_f32 v[8:9], v[8:9], v[66:67] op_sel_hi:[1,0]
	v_pk_mul_f32 v[6:7], v[6:7], v[66:67] op_sel_hi:[1,0]
	v_pk_mul_f32 v[4:5], v[4:5], v[66:67] op_sel_hi:[1,0]
	v_pk_mul_f32 v[2:3], v[2:3], v[66:67] op_sel_hi:[1,0]

.Lprio_8:
	v_add_u32_e32 v99, s4, v94
	s_waitcnt vmcnt(0)
	ds_read_b128 v[34:37], v99
	v_add_u32_e32 v98, s4, v93
	ds_read_b128 v[102:105], v98
	ds_read_b128 v[50:53], v99 offset:4096
	v_add_u32_e32 v97, s4, v92
	v_add_u32_e32 v95, s4, v91
	s_waitcnt lgkmcnt(0)
	v_mfma_f32_32x32x16_bf16 v[34:49], v[34:37], v[66:69], 0
	v_mfma_f32_32x32x16_bf16 v[34:49], v[102:105], v[70:73], v[34:49]
	ds_read_b128 v[102:105], v98 offset:4096
	v_mfma_f32_32x32x16_bf16 v[50:65], v[50:53], v[66:69], 0
	s_waitcnt lgkmcnt(0)
	v_mfma_f32_32x32x16_bf16 v[50:65], v[102:105], v[70:73], v[50:65]
	ds_read_b128 v[102:105], v97
	s_waitcnt lgkmcnt(0)
	v_mfma_f32_32x32x16_bf16 v[34:49], v[102:105], v[74:77], v[34:49]
	ds_read_b128 v[102:105], v97 offset:4096
	s_waitcnt lgkmcnt(0)
	v_mfma_f32_32x32x16_bf16 v[50:65], v[102:105], v[74:77], v[50:65]
	ds_read_b128 v[102:105], v95 offset:4096
	s_waitcnt lgkmcnt(0)
	v_mfma_f32_32x32x16_bf16 v[50:65], v[102:105], v[78:81], v[50:65]
	ds_read_b128 v[102:105], v95
	s_waitcnt lgkmcnt(0)
	v_mfma_f32_32x32x16_bf16 v[34:49], v[102:105], v[78:81], v[34:49]
	v_cmp_gt_u32_e32 vcc, 0x100, v206
	s_setprio 0
	s_cbranch_vccz .Lprio_7
	s_setprio 1
.Lprio_7:
	s_nop 8
	v_max_f32_e32 v0, v51, v51
	s_nop 1
	v_max_f32_e32 v96, v35, v35
	v_max_f32_e32 v0, v96, v0
	v_max_f32_e32 v96, v52, v52
	v_max_f32_e32 v102, v36, v36
	v_max_f32_e32 v96, v102, v96
	v_max_f32_e32 v102, v53, v53
	v_max_f32_e32 v103, v37, v37
	v_max3_f32 v0, v34, v50, v0
	v_max_f32_e32 v102, v103, v102
	v_max3_f32 v0, v0, v96, v102
	v_max_f32_e32 v96, v54, v54
	v_max_f32_e32 v102, v38, v38
	v_max_f32_e32 v96, v102, v96
	v_max_f32_e32 v102, v55, v55
	v_max_f32_e32 v103, v39, v39
	v_max_f32_e32 v102, v103, v102
	v_max3_f32 v0, v0, v96, v102
	v_max_f32_e32 v96, v56, v56
	v_max_f32_e32 v102, v40, v40
	v_max_f32_e32 v96, v102, v96
	v_max_f32_e32 v102, v57, v57
	v_max_f32_e32 v103, v41, v41
	v_max_f32_e32 v102, v103, v102
	v_max3_f32 v0, v0, v96, v102
	v_max_f32_e32 v96, v58, v58
	v_max_f32_e32 v102, v42, v42
	v_max_f32_e32 v96, v102, v96
	v_max_f32_e32 v102, v59, v59
	v_max_f32_e32 v103, v43, v43
	v_max_f32_e32 v102, v103, v102
	v_max3_f32 v0, v0, v96, v102
	v_max_f32_e32 v96, v60, v60
	v_max_f32_e32 v102, v44, v44
	v_max_f32_e32 v96, v102, v96
	v_max_f32_e32 v102, v61, v61
	v_max_f32_e32 v103, v45, v45
	v_max_f32_e32 v102, v103, v102
	v_max3_f32 v0, v0, v96, v102
	v_max_f32_e32 v96, v62, v62
	v_max_f32_e32 v102, v46, v46
	v_max_f32_e32 v96, v102, v96
	v_max_f32_e32 v102, v63, v63
	v_max_f32_e32 v103, v47, v47
	v_max_f32_e32 v102, v103, v102
	v_max3_f32 v0, v0, v96, v102
	v_max_f32_e32 v96, v64, v64
	v_max_f32_e32 v102, v48, v48
	v_max_f32_e32 v96, v102, v96
	v_max_f32_e32 v102, v65, v65
	v_max_f32_e32 v103, v49, v49
	v_max_f32_e32 v102, v103, v102
	v_max3_f32 v0, v0, v96, v102
	v_and_b32_e32 v102, 64, v221
	v_xor_b32_e32 v96, 32, v221
	v_add_u32_e32 v102, 64, v102
	v_cmp_lt_i32_e32 vcc, v96, v102
	s_nop 1
	v_cndmask_b32_e32 v96, v221, v96, vcc
	v_lshlrev_b32_e32 v102, 2, v96
	ds_bpermute_b32 v96, v102, v0
	s_waitcnt lgkmcnt(0)
	v_max3_f32 v96, v101, v0, v96
	v_sub_f32_e32 v0, v34, v96
	v_exp_f32_e32 v34, v0
	v_sub_f32_e32 v0, v50, v96
	v_exp_f32_e32 v50, v0
	v_sub_f32_e32 v0, v35, v96
	v_exp_f32_e32 v35, v0
	v_sub_f32_e32 v0, v51, v96
	v_exp_f32_e32 v51, v0
	v_sub_f32_e32 v36, v36, v96
	v_sub_f32_e32 v52, v52, v96
	v_exp_f32_e32 v36, v36
	v_exp_f32_e32 v52, v52
	v_sub_f32_e32 v0, v101, v96
	v_add_f32_e32 v101, v34, v50
	v_add_f32_e32 v101, 0, v101
	v_add_f32_e32 v103, v35, v51
	v_add_f32_e32 v101, v103, v101
	v_add_f32_e32 v103, v36, v52
	v_sub_f32_e32 v38, v38, v96
	v_sub_f32_e32 v37, v37, v96
	v_sub_f32_e32 v53, v53, v96
	v_add_f32_e32 v103, v103, v101
	v_exp_f32_e32 v101, v38
	v_sub_f32_e32 v38, v54, v96
	v_exp_f32_e32 v37, v37
	v_exp_f32_e32 v53, v53
	v_exp_f32_e32 v54, v38
	v_sub_f32_e32 v38, v39, v96
	v_exp_f32_e32 v39, v38
	v_sub_f32_e32 v38, v55, v96
	v_exp_f32_e32 v55, v38
	v_sub_f32_e32 v40, v40, v96
	v_sub_f32_e32 v56, v56, v96
	v_exp_f32_e32 v40, v40
	v_exp_f32_e32 v56, v56
	v_sub_f32_e32 v41, v41, v96
	v_sub_f32_e32 v57, v57, v96
	v_add_f32_e32 v104, v37, v53
	v_exp_f32_e32 v41, v41
	v_exp_f32_e32 v57, v57
	v_sub_f32_e32 v42, v42, v96
	v_sub_f32_e32 v58, v58, v96
	v_add_f32_e32 v38, v104, v103
	v_add_f32_e32 v103, v101, v54
	v_exp_f32_e32 v42, v42
	v_exp_f32_e32 v58, v58
	v_sub_f32_e32 v43, v43, v96
	v_sub_f32_e32 v59, v59, v96
	v_add_f32_e32 v38, v103, v38
	v_add_f32_e32 v103, v39, v55
	v_exp_f32_e32 v43, v43
	v_exp_f32_e32 v59, v59
	v_sub_f32_e32 v44, v44, v96
	v_sub_f32_e32 v60, v60, v96
	v_add_f32_e32 v38, v103, v38
	v_add_f32_e32 v103, v40, v56
	v_exp_f32_e32 v44, v44
	v_exp_f32_e32 v60, v60
	v_sub_f32_e32 v45, v45, v96
	v_sub_f32_e32 v61, v61, v96
	v_add_f32_e32 v38, v103, v38
	v_add_f32_e32 v103, v41, v57
	v_exp_f32_e32 v45, v45
	v_exp_f32_e32 v61, v61
	v_sub_f32_e32 v46, v46, v96
	v_sub_f32_e32 v62, v62, v96
	v_add_f32_e32 v38, v103, v38
	v_add_f32_e32 v103, v42, v58
	v_exp_f32_e32 v46, v46
	v_exp_f32_e32 v62, v62
	v_sub_f32_e32 v47, v47, v96
	v_sub_f32_e32 v63, v63, v96
	v_add_f32_e32 v38, v103, v38
	v_add_f32_e32 v103, v43, v59
	v_exp_f32_e32 v47, v47
	v_exp_f32_e32 v63, v63
	v_sub_f32_e32 v48, v48, v96
	v_sub_f32_e32 v64, v64, v96
	v_add_f32_e32 v38, v103, v38
	v_add_f32_e32 v103, v44, v60
	v_exp_f32_e32 v48, v48
	v_exp_f32_e32 v64, v64
	v_sub_f32_e32 v49, v49, v96
	v_sub_f32_e32 v65, v65, v96
	v_add_f32_e32 v38, v103, v38
	v_add_f32_e32 v103, v45, v61
	v_exp_f32_e32 v49, v49
	v_exp_f32_e32 v65, v65
	v_add_f32_e32 v38, v103, v38
	v_add_f32_e32 v103, v46, v62
	v_add_f32_e32 v38, v103, v38
	v_add_f32_e32 v103, v47, v63
	v_add_f32_e32 v38, v103, v38
	v_add_f32_e32 v103, v48, v64
	v_add_f32_e32 v38, v103, v38
	v_add_f32_e32 v103, v49, v65
	v_add_f32_e32 v38, v103, v38
	v_exp_f32_e32 v0, v0
	ds_bpermute_b32 v102, v102, v38
	v_cmp_neq_f32_e32 vcc, 1.0, v0
	s_cbranch_vccz .LBB0_371
	v_pk_mul_f32 v[32:33], v[32:33], v[0:1] op_sel_hi:[1,0]
	v_pk_mul_f32 v[30:31], v[30:31], v[0:1] op_sel_hi:[1,0]
	v_pk_mul_f32 v[28:29], v[28:29], v[0:1] op_sel_hi:[1,0]
	v_pk_mul_f32 v[26:27], v[26:27], v[0:1] op_sel_hi:[1,0]
	v_pk_mul_f32 v[24:25], v[24:25], v[0:1] op_sel_hi:[1,0]
	v_pk_mul_f32 v[22:23], v[22:23], v[0:1] op_sel_hi:[1,0]
	v_pk_mul_f32 v[20:21], v[20:21], v[0:1] op_sel_hi:[1,0]
	v_pk_mul_f32 v[18:19], v[18:19], v[0:1] op_sel_hi:[1,0]
	v_pk_mul_f32 v[16:17], v[16:17], v[0:1] op_sel_hi:[1,0]
	v_pk_mul_f32 v[14:15], v[14:15], v[0:1] op_sel_hi:[1,0]
	v_pk_mul_f32 v[12:13], v[12:13], v[0:1] op_sel_hi:[1,0]
	v_pk_mul_f32 v[10:11], v[10:11], v[0:1] op_sel_hi:[1,0]
	v_pk_mul_f32 v[8:9], v[8:9], v[0:1] op_sel_hi:[1,0]
	v_pk_mul_f32 v[6:7], v[6:7], v[0:1] op_sel_hi:[1,0]
	v_pk_mul_f32 v[4:5], v[4:5], v[0:1] op_sel_hi:[1,0]
	v_pk_mul_f32 v[2:3], v[2:3], v[0:1] op_sel_hi:[1,0]

.LBB0_400:
	s_andn2_b64 vcc, exec, s[4:5]
	s_cbranch_vccnz .LBB0_408
	v_cmp_gt_u32_e32 vcc, 0x100, v206
	s_setprio 2
	s_cbranch_vccz .Lprio_14
	s_setprio 3
.Lprio_14:
	s_and_b32 s8, s17, 0xc000
	v_or_b32_e32 v50, s8, v94
	s_waitcnt vmcnt(0)
	ds_read_b128 v[34:37], v50
	v_or_b32_e32 v101, s8, v95
	ds_read_b128 v[102:105], v101
	ds_read_b128 v[50:53], v50 offset:4096
	s_andn2_b64 vcc, exec, s[0:1]
	s_waitcnt lgkmcnt(0)
	v_mfma_f32_32x32x16_bf16 v[34:49], v[34:37], v[66:69], 0
	v_mfma_f32_32x32x16_bf16 v[34:49], v[102:105], v[70:73], v[34:49]
	ds_read_b128 v[102:105], v101 offset:4096
	v_or_b32_e32 v101, s8, v96
	v_mfma_f32_32x32x16_bf16 v[50:65], v[50:53], v[66:69], 0
	s_waitcnt lgkmcnt(0)
	v_mfma_f32_32x32x16_bf16 v[50:65], v[102:105], v[70:73], v[50:65]
	ds_read_b128 v[102:105], v101
	s_waitcnt lgkmcnt(0)
	v_mfma_f32_32x32x16_bf16 v[34:49], v[102:105], v[74:77], v[34:49]
	ds_read_b128 v[102:105], v101 offset:4096
	v_or_b32_e32 v101, s8, v97
	s_waitcnt lgkmcnt(0)
	v_mfma_f32_32x32x16_bf16 v[50:65], v[102:105], v[74:77], v[50:65]
	ds_read_b128 v[102:105], v101
	s_waitcnt lgkmcnt(0)
	v_mfma_f32_32x32x16_bf16 v[34:49], v[102:105], v[78:81], v[34:49]
	ds_read_b128 v[102:105], v101 offset:4096
	s_waitcnt lgkmcnt(0)
	v_mfma_f32_32x32x16_bf16 v[50:65], v[102:105], v[78:81], v[50:65]
	s_cbranch_vccnz .LBB0_405
	s_lshl_b32 s0, s54, 6
	s_sub_i32 s1, s9, s10
	s_add_i32 s0, s1, s0
	s_addk_i32 s0, 0xf000
	v_sub_u32_e32 v101, s0, v91
	v_add_u32_e32 v101, 63, v101
	v_subrev_u32_e32 v102, s0, v98
	v_max_i32_e32 v101, v101, v102
	s_movk_i32 s1, 0x80
	v_cmp_lt_i32_e32 vcc, s1, v101
	s_and_saveexec_b64 s[4:5], vcc
	s_cbranch_execz .LBB0_404
	v_add_u32_e32 v101, s0, v99
	s_movk_i32 s0, 0x101
	v_cmp_gt_u32_e32 vcc, s0, v101
	v_add_u32_e32 v102, 0xffffff1f, v101
	s_movk_i32 s0, 0xfefe
	v_cndmask_b32_e32 v34, v215, v34, vcc
	v_cmp_lt_u32_e32 vcc, s0, v102
	v_add_u32_e32 v102, 0xffffff00, v101
	s_nop 0
	v_cndmask_b32_e32 v50, v215, v50, vcc
	v_cmp_lt_u32_e32 vcc, s0, v102
	v_add_u32_e32 v102, 0xffffff20, v101
	s_nop 0
	v_cndmask_b32_e32 v35, v215, v35, vcc
	v_cmp_lt_u32_e32 vcc, s0, v102
	v_add_u32_e32 v102, 0xffffff01, v101
	s_nop 0
	v_cndmask_b32_e32 v51, v215, v51, vcc
	v_cmp_lt_u32_e32 vcc, s0, v102
	v_add_u32_e32 v102, 0xffffff21, v101
	s_nop 0
	v_cndmask_b32_e32 v36, v215, v36, vcc
	v_cmp_lt_u32_e32 vcc, s0, v102
	v_add_u32_e32 v102, 0xffffff02, v101
	s_nop 0
	v_cndmask_b32_e32 v52, v215, v52, vcc
	v_cmp_lt_u32_e32 vcc, s0, v102
	v_add_u32_e32 v102, 0xffffff22, v101
	s_nop 0
	v_cndmask_b32_e32 v37, v215, v37, vcc
	v_cmp_lt_u32_e32 vcc, s0, v102
	v_add_u32_e32 v102, 0xffffff07, v101
	s_nop 0
	v_cndmask_b32_e32 v53, v215, v53, vcc
	v_cmp_lt_u32_e32 vcc, s0, v102
	v_add_u32_e32 v102, 0xffffff27, v101
	s_nop 0
	v_cndmask_b32_e32 v38, v215, v38, vcc
	v_cmp_lt_u32_e32 vcc, s0, v102
	v_add_u32_e32 v102, 0xffffff08, v101
	s_nop 0
	v_cndmask_b32_e32 v54, v215, v54, vcc
	v_cmp_lt_u32_e32 vcc, s0, v102
	v_add_u32_e32 v102, 0xffffff28, v101
	s_nop 0
	v_cndmask_b32_e32 v39, v215, v39, vcc
	v_cmp_lt_u32_e32 vcc, s0, v102
	v_add_u32_e32 v102, 0xffffff09, v101
	s_nop 0
	v_cndmask_b32_e32 v55, v215, v55, vcc
	v_cmp_lt_u32_e32 vcc, s0, v102
	v_add_u32_e32 v102, 0xffffff29, v101
	s_nop 0
	v_cndmask_b32_e32 v40, v215, v40, vcc
	v_cmp_lt_u32_e32 vcc, s0, v102
	v_add_u32_e32 v102, 0xffffff0a, v101
	s_nop 0
	v_cndmask_b32_e32 v56, v215, v56, vcc
	v_cmp_lt_u32_e32 vcc, s0, v102
	v_add_u32_e32 v102, 0xffffff2a, v101
	s_nop 0
	v_cndmask_b32_e32 v41, v215, v41, vcc
	v_cmp_lt_u32_e32 vcc, s0, v102
	v_add_u32_e32 v102, 0xffffff0f, v101
	s_nop 0
	v_cndmask_b32_e32 v57, v215, v57, vcc
	v_cmp_lt_u32_e32 vcc, s0, v102
	v_add_u32_e32 v102, 0xffffff2f, v101
	s_nop 0
	v_cndmask_b32_e32 v42, v215, v42, vcc
	v_cmp_lt_u32_e32 vcc, s0, v102
	v_add_u32_e32 v102, 0xffffff10, v101
	s_nop 0
	v_cndmask_b32_e32 v58, v215, v58, vcc
	v_cmp_lt_u32_e32 vcc, s0, v102
	v_add_u32_e32 v102, 0xffffff30, v101
	s_nop 0
	v_cndmask_b32_e32 v43, v215, v43, vcc
	v_cmp_lt_u32_e32 vcc, s0, v102
	v_add_u32_e32 v102, 0xffffff11, v101
	s_nop 0
	v_cndmask_b32_e32 v59, v215, v59, vcc
	v_cmp_lt_u32_e32 vcc, s0, v102
	v_add_u32_e32 v102, 0xffffff31, v101
	s_nop 0
	v_cndmask_b32_e32 v44, v215, v44, vcc
	v_cmp_lt_u32_e32 vcc, s0, v102
	v_add_u32_e32 v102, 0xffffff12, v101
	s_nop 0
	v_cndmask_b32_e32 v60, v215, v60, vcc
	v_cmp_lt_u32_e32 vcc, s0, v102
	v_add_u32_e32 v102, 0xffffff32, v101
	s_nop 0
	v_cndmask_b32_e32 v45, v215, v45, vcc
	v_cmp_lt_u32_e32 vcc, s0, v102
	v_add_u32_e32 v102, 0xffffff17, v101
	s_nop 0
	v_cndmask_b32_e32 v61, v215, v61, vcc
	v_cmp_lt_u32_e32 vcc, s0, v102
	v_add_u32_e32 v102, 0xffffff37, v101
	s_nop 0
	v_cndmask_b32_e32 v46, v215, v46, vcc
	v_cmp_lt_u32_e32 vcc, s0, v102
	v_add_u32_e32 v102, 0xffffff18, v101
	s_nop 0
	v_cndmask_b32_e32 v62, v215, v62, vcc
	v_cmp_lt_u32_e32 vcc, s0, v102
	v_add_u32_e32 v102, 0xffffff38, v101
	s_nop 0
	v_cndmask_b32_e32 v47, v215, v47, vcc
	v_cmp_lt_u32_e32 vcc, s0, v102
	v_add_u32_e32 v102, 0xffffff19, v101
	s_nop 0
	v_cndmask_b32_e32 v63, v215, v63, vcc
	v_cmp_lt_u32_e32 vcc, s0, v102
	v_add_u32_e32 v102, 0xffffff39, v101
	s_nop 0
	v_cndmask_b32_e32 v48, v215, v48, vcc
	v_cmp_lt_u32_e32 vcc, s0, v102
	v_add_u32_e32 v102, 0xffffff1a, v101
	v_add_u32_e32 v101, 0xffffff3a, v101
	v_cndmask_b32_e32 v64, v215, v64, vcc
	v_cmp_lt_u32_e32 vcc, s0, v102
	s_nop 1
	v_cndmask_b32_e32 v49, v215, v49, vcc
	v_cmp_lt_u32_e32 vcc, s0, v101
	s_nop 1
	v_cndmask_b32_e32 v65, v215, v65, vcc

.LBB0_405:
	v_cmp_gt_u32_e32 vcc, 0x100, v206
	s_setprio 0
	s_cbranch_vccz .Lprio_13
	s_setprio 1

.Lprio_11:
	s_mul_i32 s0, s12, 0xa000
	v_add_u32_e32 v187, s0, v178
	v_add_u32_e32 v189, s0, v180
	v_add_u32_e32 v194, s0, v182
	v_add_u32_e32 v195, s0, v184
	ds_read_b128 v[196:199], v187
	ds_read_b128 v[200:203], v189
	ds_read_b128 v[232:235], v187 offset:12288
	ds_read_b128 v[236:239], v189 offset:12288
	ds_read_b128 v[240:243], v194
	s_waitcnt lgkmcnt(4)
	v_mfma_f32_32x32x16_bf16 v[66:81], v[196:199], v[98:101], 0
	ds_read_b128 v[244:247], v194 offset:12288
	s_waitcnt lgkmcnt(4)
	v_mfma_f32_32x32x16_bf16 v[66:81], v[200:203], v[102:105], v[66:81]
	ds_read_b128 v[196:199], v195
	s_waitcnt lgkmcnt(4)
	v_mfma_f32_32x32x16_bf16 v[82:97], v[232:235], v[98:101], 0
	ds_read_b128 v[200:203], v195 offset:12288
	s_waitcnt lgkmcnt(4)
	v_mfma_f32_32x32x16_bf16 v[82:97], v[236:239], v[102:105], v[82:97]
	ds_read_b128 v[232:235], v187 offset:128
	s_waitcnt lgkmcnt(4)
	v_mfma_f32_32x32x16_bf16 v[66:81], v[240:243], v[106:109], v[66:81]
	ds_read_b128 v[236:239], v187 offset:12416
	s_waitcnt lgkmcnt(4)
	v_mfma_f32_32x32x16_bf16 v[82:97], v[244:247], v[106:109], v[82:97]
	ds_read_b128 v[240:243], v189 offset:128
	s_waitcnt lgkmcnt(4)
	v_mfma_f32_32x32x16_bf16 v[66:81], v[196:199], v[110:113], v[66:81]
	ds_read_b128 v[244:247], v189 offset:12416
	s_waitcnt lgkmcnt(4)
	v_mfma_f32_32x32x16_bf16 v[82:97], v[200:203], v[110:113], v[82:97]
	ds_read_b128 v[196:199], v194 offset:128
	s_waitcnt lgkmcnt(4)
	v_mfma_f32_32x32x16_bf16 v[66:81], v[232:235], v[114:117], v[66:81]
	ds_read_b128 v[200:203], v194 offset:12416
	s_waitcnt lgkmcnt(4)
	v_mfma_f32_32x32x16_bf16 v[82:97], v[236:239], v[114:117], v[82:97]
	ds_read_b128 v[232:235], v195 offset:128
	s_waitcnt lgkmcnt(4)
	v_mfma_f32_32x32x16_bf16 v[66:81], v[240:243], v[118:121], v[66:81]
	ds_read_b128 v[236:239], v195 offset:12416
	s_waitcnt lgkmcnt(4)
	v_mfma_f32_32x32x16_bf16 v[82:97], v[244:247], v[118:121], v[82:97]
	ds_read_b128 v[240:243], v187 offset:256
	s_waitcnt lgkmcnt(4)
	v_mfma_f32_32x32x16_bf16 v[66:81], v[196:199], v[122:125], v[66:81]
	ds_read_b128 v[244:247], v187 offset:12544
	s_waitcnt lgkmcnt(4)
	v_mfma_f32_32x32x16_bf16 v[82:97], v[200:203], v[122:125], v[82:97]
	ds_read_b128 v[196:199], v189 offset:256
	s_waitcnt lgkmcnt(4)
	v_mfma_f32_32x32x16_bf16 v[66:81], v[232:235], v[126:129], v[66:81]
	ds_read_b128 v[200:203], v189 offset:12544
	s_waitcnt lgkmcnt(4)
	v_mfma_f32_32x32x16_bf16 v[82:97], v[236:239], v[126:129], v[82:97]
	ds_read_b128 v[232:235], v194 offset:256
	s_waitcnt lgkmcnt(4)
	v_mfma_f32_32x32x16_bf16 v[66:81], v[240:243], v[130:133], v[66:81]
	ds_read_b128 v[236:239], v194 offset:12544
	s_waitcnt lgkmcnt(4)
	v_mfma_f32_32x32x16_bf16 v[82:97], v[244:247], v[130:133], v[82:97]
	ds_read_b128 v[240:243], v195 offset:12544
	s_waitcnt lgkmcnt(4)
	v_mfma_f32_32x32x16_bf16 v[66:81], v[196:199], v[134:137], v[66:81]
	ds_read_b128 v[244:247], v195 offset:256
	s_waitcnt lgkmcnt(4)
	v_mfma_f32_32x32x16_bf16 v[82:97], v[200:203], v[134:137], v[82:97]
	s_waitcnt lgkmcnt(3)
	v_mfma_f32_32x32x16_bf16 v[66:81], v[232:235], v[138:141], v[66:81]
	s_waitcnt lgkmcnt(2)
	v_mfma_f32_32x32x16_bf16 v[82:97], v[236:239], v[138:141], v[82:97]
	s_waitcnt lgkmcnt(1)
	v_mfma_f32_32x32x16_bf16 v[82:97], v[240:243], v[142:145], v[82:97]
	s_waitcnt lgkmcnt(0)
	v_mfma_f32_32x32x16_bf16 v[66:81], v[244:247], v[142:145], v[66:81]
	v_cmp_gt_u32_e32 vcc, 0x100, v206
	s_setprio 0
	s_cbranch_vccz .Lprio_10
	s_setprio 1
.Lprio_10:
	s_nop 1
	s_nop 8
	v_max_f32_e32 v187, v83, v83
	s_nop 1
	v_max_f32_e32 v189, v67, v67
	v_max_f32_e32 v187, v189, v187
	v_max_f32_e32 v189, v84, v84
	v_max_f32_e32 v190, v68, v68
	v_max_f32_e32 v189, v190, v189
	v_max_f32_e32 v190, v85, v85
	v_max_f32_e32 v191, v69, v69
	v_max3_f32 v187, v66, v82, v187
	v_max_f32_e32 v190, v191, v190
	v_max3_f32 v187, v187, v189, v190
	v_max_f32_e32 v189, v86, v86
	v_max_f32_e32 v190, v70, v70
	v_max_f32_e32 v189, v190, v189
	v_max_f32_e32 v190, v87, v87
	v_max_f32_e32 v191, v71, v71
	v_max_f32_e32 v190, v191, v190
	v_max3_f32 v187, v187, v189, v190
	v_max_f32_e32 v189, v88, v88
	v_max_f32_e32 v190, v72, v72
	v_max_f32_e32 v189, v190, v189
	v_max_f32_e32 v190, v89, v89
	v_max_f32_e32 v191, v73, v73
	v_max_f32_e32 v190, v191, v190
	v_max3_f32 v187, v187, v189, v190
	v_max_f32_e32 v189, v90, v90
	v_max_f32_e32 v190, v74, v74
	v_max_f32_e32 v189, v190, v189
	v_max_f32_e32 v190, v91, v91
	v_max_f32_e32 v191, v75, v75
	v_max_f32_e32 v190, v191, v190
	v_max3_f32 v187, v187, v189, v190
	v_max_f32_e32 v189, v92, v92
	v_max_f32_e32 v190, v76, v76
	v_max_f32_e32 v189, v190, v189
	v_max_f32_e32 v190, v93, v93
	v_max_f32_e32 v191, v77, v77
	v_max_f32_e32 v190, v191, v190
	v_max3_f32 v187, v187, v189, v190
	v_max_f32_e32 v189, v94, v94
	v_max_f32_e32 v190, v78, v78
	v_max_f32_e32 v189, v190, v189
	v_max_f32_e32 v190, v95, v95
	v_max_f32_e32 v191, v79, v79
	v_max_f32_e32 v190, v191, v190
	v_max3_f32 v187, v187, v189, v190
	v_max_f32_e32 v189, v96, v96
	v_max_f32_e32 v190, v80, v80
	v_max_f32_e32 v189, v190, v189
	v_max_f32_e32 v190, v97, v97
	v_max_f32_e32 v191, v81, v81
	v_max_f32_e32 v190, v191, v190
	v_max3_f32 v187, v187, v189, v190
	v_and_b32_e32 v190, 64, v221
	v_xor_b32_e32 v189, 32, v221
	v_add_u32_e32 v190, 64, v190
	v_cmp_lt_i32_e32 vcc, v189, v190
	s_nop 1
	v_cndmask_b32_e32 v189, v221, v189, vcc
	v_lshlrev_b32_e32 v195, 2, v189
	ds_bpermute_b32 v189, v195, v187
	s_waitcnt lgkmcnt(0)
	v_max3_f32 v187, v188, v187, v189
	v_sub_f32_e32 v66, v66, v187
	v_exp_f32_e32 v189, v66
	v_sub_f32_e32 v66, v82, v187
	v_exp_f32_e32 v190, v66
	v_sub_f32_e32 v66, v67, v187
	v_exp_f32_e32 v67, v66
	v_sub_f32_e32 v66, v83, v187
	v_exp_f32_e32 v83, v66
	v_sub_f32_e32 v68, v68, v187
	v_sub_f32_e32 v84, v84, v187
	v_exp_f32_e32 v68, v68
	v_exp_f32_e32 v84, v84
	v_add_f32_e32 v82, v189, v190
	v_sub_f32_e32 v69, v69, v187
	v_sub_f32_e32 v85, v85, v187
	v_sub_f32_e32 v66, v188, v187
	v_add_f32_e32 v82, 0, v82
	v_add_f32_e32 v188, v67, v83
	v_exp_f32_e32 v69, v69
	v_exp_f32_e32 v85, v85
	v_add_f32_e32 v82, v188, v82
	v_add_f32_e32 v188, v68, v84
	v_sub_f32_e32 v70, v70, v187
	v_add_f32_e32 v82, v188, v82
	v_exp_f32_e32 v188, v70
	v_sub_f32_e32 v70, v86, v187
	v_exp_f32_e32 v86, v70
	v_sub_f32_e32 v70, v71, v187
	v_add_f32_e32 v192, v69, v85
	v_exp_f32_e32 v191, v70
	v_sub_f32_e32 v70, v87, v187
	v_sub_f32_e32 v72, v72, v187
	v_exp_f32_e32 v87, v70
	v_add_f32_e32 v70, v192, v82
	v_exp_f32_e32 v192, v72
	v_sub_f32_e32 v72, v88, v187
	v_exp_f32_e32 v88, v72
	v_add_f32_e32 v71, v188, v86
	v_add_f32_e32 v70, v71, v70
	v_add_f32_e32 v71, v191, v87
	v_sub_f32_e32 v72, v73, v187
	v_exp_f32_e32 v73, v72
	v_sub_f32_e32 v72, v89, v187
	v_add_f32_e32 v70, v71, v70
	v_add_f32_e32 v71, v192, v88
	v_exp_f32_e32 v89, v72
	v_add_f32_e32 v82, v71, v70
	v_sub_f32_e32 v70, v74, v187
	v_sub_f32_e32 v71, v90, v187
	v_exp_f32_e32 v70, v70
	v_exp_f32_e32 v71, v71
	v_sub_f32_e32 v72, v75, v187
	v_sub_f32_e32 v74, v91, v187
	v_exp_f32_e32 v72, v72
	v_exp_f32_e32 v75, v74
	v_sub_f32_e32 v76, v76, v187
	v_sub_f32_e32 v90, v92, v187
	v_sub_f32_e32 v78, v78, v187
	v_exp_f32_e32 v76, v76
	v_exp_f32_e32 v90, v90
	v_sub_f32_e32 v77, v77, v187
	v_sub_f32_e32 v91, v93, v187
	v_exp_f32_e32 v92, v78
	v_sub_f32_e32 v78, v94, v187
	v_add_f32_e32 v193, v73, v89
	v_exp_f32_e32 v77, v77
	v_exp_f32_e32 v91, v91
	v_exp_f32_e32 v93, v78
	v_sub_f32_e32 v78, v79, v187
	v_sub_f32_e32 v79, v80, v187
	v_add_f32_e32 v74, v193, v82
	v_add_f32_e32 v82, v70, v71
	v_exp_f32_e32 v94, v78
	v_sub_f32_e32 v78, v95, v187
	v_exp_f32_e32 v193, v79
	v_sub_f32_e32 v79, v96, v187
	v_add_f32_e32 v74, v82, v74
	v_add_f32_e32 v82, v72, v75
	v_exp_f32_e32 v95, v78
	v_exp_f32_e32 v96, v79
	v_sub_f32_e32 v79, v81, v187
	v_add_f32_e32 v74, v82, v74
	v_add_f32_e32 v82, v76, v90
	v_exp_f32_e32 v194, v79
	v_sub_f32_e32 v79, v97, v187
	v_add_f32_e32 v74, v82, v74
	v_add_f32_e32 v82, v77, v91
	v_exp_f32_e32 v97, v79
	v_add_f32_e32 v74, v82, v74
	v_add_f32_e32 v78, v92, v93
	v_add_f32_e32 v74, v78, v74
	v_add_f32_e32 v78, v94, v95
	v_add_f32_e32 v74, v78, v74
	v_add_f32_e32 v78, v193, v96
	v_add_f32_e32 v74, v78, v74
	v_add_f32_e32 v78, v194, v97
	v_add_f32_e32 v74, v78, v74
	v_exp_f32_e32 v66, v66
	ds_bpermute_b32 v78, v195, v74
	v_cmp_neq_f32_e32 vcc, 1.0, v66
	s_cbranch_vccz .LBB0_520
	v_pk_mul_f32 v[64:65], v[64:65], v[66:67] op_sel_hi:[1,0]
	v_pk_mul_f32 v[62:63], v[62:63], v[66:67] op_sel_hi:[1,0]
	v_pk_mul_f32 v[60:61], v[60:61], v[66:67] op_sel_hi:[1,0]
	v_pk_mul_f32 v[58:59], v[58:59], v[66:67] op_sel_hi:[1,0]
	v_pk_mul_f32 v[56:57], v[56:57], v[66:67] op_sel_hi:[1,0]
	v_pk_mul_f32 v[54:55], v[54:55], v[66:67] op_sel_hi:[1,0]
	v_pk_mul_f32 v[52:53], v[52:53], v[66:67] op_sel_hi:[1,0]
	v_pk_mul_f32 v[50:51], v[50:51], v[66:67] op_sel_hi:[1,0]
	v_pk_mul_f32 v[48:49], v[48:49], v[66:67] op_sel_hi:[1,0]
	v_pk_mul_f32 v[46:47], v[46:47], v[66:67] op_sel_hi:[1,0]
	v_pk_mul_f32 v[44:45], v[44:45], v[66:67] op_sel_hi:[1,0]
	v_pk_mul_f32 v[42:43], v[42:43], v[66:67] op_sel_hi:[1,0]
	v_pk_mul_f32 v[40:41], v[40:41], v[66:67] op_sel_hi:[1,0]
	v_pk_mul_f32 v[38:39], v[38:39], v[66:67] op_sel_hi:[1,0]
	v_pk_mul_f32 v[36:37], v[36:37], v[66:67] op_sel_hi:[1,0]
	v_pk_mul_f32 v[34:35], v[34:35], v[66:67] op_sel_hi:[1,0]
	v_pk_mul_f32 v[32:33], v[32:33], v[66:67] op_sel_hi:[1,0]
	v_pk_mul_f32 v[30:31], v[30:31], v[66:67] op_sel_hi:[1,0]
	v_pk_mul_f32 v[28:29], v[28:29], v[66:67] op_sel_hi:[1,0]
	v_pk_mul_f32 v[26:27], v[26:27], v[66:67] op_sel_hi:[1,0]
	v_pk_mul_f32 v[24:25], v[24:25], v[66:67] op_sel_hi:[1,0]
	v_pk_mul_f32 v[22:23], v[22:23], v[66:67] op_sel_hi:[1,0]
	v_pk_mul_f32 v[20:21], v[20:21], v[66:67] op_sel_hi:[1,0]
	v_pk_mul_f32 v[18:19], v[18:19], v[66:67] op_sel_hi:[1,0]
	v_pk_mul_f32 v[16:17], v[16:17], v[66:67] op_sel_hi:[1,0]
	v_pk_mul_f32 v[14:15], v[14:15], v[66:67] op_sel_hi:[1,0]
	v_pk_mul_f32 v[12:13], v[12:13], v[66:67] op_sel_hi:[1,0]
	v_pk_mul_f32 v[10:11], v[10:11], v[66:67] op_sel_hi:[1,0]
	v_pk_mul_f32 v[8:9], v[8:9], v[66:67] op_sel_hi:[1,0]
	v_pk_mul_f32 v[6:7], v[6:7], v[66:67] op_sel_hi:[1,0]
	v_pk_mul_f32 v[4:5], v[4:5], v[66:67] op_sel_hi:[1,0]
	v_pk_mul_f32 v[2:3], v[2:3], v[66:67] op_sel_hi:[1,0]

.LBB0_1030:
	s_setprio 0
	v_readlane_b32 s6, v254, 52
	s_mov_b64 s[4:5], -1
	s_mov_b64 s[0:1], 0
	s_cmp_lt_i32 s6, 22
	s_mov_b64 s[6:7], 0
	s_cbranch_scc1 .LBB0_1032
	v_readlane_b32 s6, v254, 52
	s_cmp_lg_u32 s6, 22
	s_mov_b64 s[4:5], 0
	s_cselect_b64 s[6:7], -1, 0
